# v8 + phase D select: branch-free software-pipelined compaction loop (fast path), verified slot-for-slot against the original loop in a side build
# speedup vs baseline: 1.0256x; 1.0099x over previous
.LBB0_702:
	s_or_b64 exec, exec, s[30:31]
	v_sub_u32_e32 v1, v1, v0
	ds_bpermute_b32 v2, v15, v0
	ds_bpermute_b32 v3, v15, v1
	s_waitcnt lgkmcnt(1)
	v_cndmask_b32_e64 v2, v2, 0, s[6:7]
	s_waitcnt lgkmcnt(0)
	v_cndmask_b32_e64 v3, v3, 0, s[6:7]
	v_add_u32_e32 v2, v2, v0
	v_add_u32_e32 v3, v3, v1
	ds_bpermute_b32 v15, v14, v2
	ds_bpermute_b32 v14, v14, v3
	s_waitcnt lgkmcnt(1)
	v_cndmask_b32_e64 v15, v15, 0, s[8:9]
	s_waitcnt lgkmcnt(0)
	v_cndmask_b32_e64 v14, v14, 0, s[8:9]
	v_add_u32_e32 v2, v15, v2
	v_add_u32_e32 v3, v14, v3
	ds_bpermute_b32 v14, v13, v2
	ds_bpermute_b32 v13, v13, v3
	s_waitcnt lgkmcnt(1)
	v_cndmask_b32_e64 v14, v14, 0, s[10:11]
	s_waitcnt lgkmcnt(0)
	v_cndmask_b32_e64 v13, v13, 0, s[10:11]
	v_add_u32_e32 v2, v14, v2
	v_add_u32_e32 v3, v13, v3
	ds_bpermute_b32 v13, v12, v2
	ds_bpermute_b32 v12, v12, v3
	s_waitcnt lgkmcnt(1)
	v_cndmask_b32_e64 v13, v13, 0, s[12:13]
	s_waitcnt lgkmcnt(0)
	v_cndmask_b32_e64 v12, v12, 0, s[12:13]
	v_add_u32_e32 v2, v13, v2
	v_add_u32_e32 v3, v12, v3
	ds_bpermute_b32 v12, v11, v2
	ds_bpermute_b32 v11, v11, v3
	s_waitcnt lgkmcnt(1)
	v_cndmask_b32_e64 v12, v12, 0, s[14:15]
	s_waitcnt lgkmcnt(0)
	v_cndmask_b32_e64 v11, v11, 0, s[14:15]
	v_add_u32_e32 v2, v12, v2
	v_add_u32_e32 v11, v11, v3
	ds_bpermute_b32 v3, v7, v2
	ds_bpermute_b32 v7, v7, v11
	s_and_saveexec_b64 s[20:21], s[0:1]
	s_cbranch_execz .LBB0_729
	s_waitcnt lgkmcnt(0)
	v_cndmask_b32_e64 v7, v7, 0, s[28:29]
	v_sub_u32_e32 v1, v11, v1
	v_add_u32_e32 v13, v1, v7
	v_cndmask_b32_e64 v1, v3, 0, s[28:29]
	v_sub_u32_e32 v0, v2, v0
	v_add_u32_e32 v7, v0, v1
	v_add_u32_e32 v11, v9, v194
	s_mov_b64 s[22:23], 0
	v_mov_b32_e32 v12, v145
	v_add_u32_e32 v15, 0x200, v8
	ds_read_b128 v[18:21], v11
.Lcp_loop:
	s_mov_b64 s[24:25], exec
	s_waitcnt lgkmcnt(0)
	v_mov_b32_e32 v0, v18
	v_mov_b32_e32 v1, v19
	v_mov_b32_e32 v2, v20
	v_mov_b32_e32 v3, v21
	v_add_u32_e32 v11, 0x400, v11
	ds_read_b128 v[18:21], v11
	v_cmp_ge_u32_e64 s[0:1], v0, v4
	v_cmp_ge_u32_e64 s[34:35], v0, v6
	v_cmp_ge_u32_e64 s[22:23], v1, v4
	v_cmp_ge_u32_e64 s[36:37], v1, v6
	v_cmp_ge_u32_e64 s[26:27], v2, v4
	v_cmp_ge_u32_e64 s[38:39], v2, v6
	v_cmp_ge_u32_e64 s[30:31], v3, v4
	v_cmp_ge_u32_e64 s[40:41], v3, v6
	v_or_b32_e32 v24, 1, v12
	v_or_b32_e32 v25, 2, v12
	v_or_b32_e32 v26, 3, v12
	v_lshl_add_u32 v14, v7, 1, v8
	v_lshl_add_u32 v31, v13, 1, v15
	s_andn2_b64 s[64:65], s[34:35], s[0:1]
	v_cndmask_b32_e64 v14, v31, v14, s[0:1]
	v_addc_co_u32_e64 v7, s[0:1], 0, v7, s[0:1]
	v_addc_co_u32_e64 v13, s[64:65], 0, v13, s[64:65]
	v_lshl_add_u32 v16, v7, 1, v8
	v_lshl_add_u32 v31, v13, 1, v15
	s_andn2_b64 s[64:65], s[36:37], s[22:23]
	v_cndmask_b32_e64 v16, v31, v16, s[22:23]
	v_addc_co_u32_e64 v7, s[22:23], 0, v7, s[22:23]
	v_addc_co_u32_e64 v13, s[64:65], 0, v13, s[64:65]
	v_lshl_add_u32 v22, v7, 1, v8
	v_lshl_add_u32 v31, v13, 1, v15
	s_andn2_b64 s[64:65], s[38:39], s[26:27]
	v_cndmask_b32_e64 v22, v31, v22, s[26:27]
	v_addc_co_u32_e64 v7, s[26:27], 0, v7, s[26:27]
	v_addc_co_u32_e64 v13, s[64:65], 0, v13, s[64:65]
	v_lshl_add_u32 v23, v7, 1, v8
	v_lshl_add_u32 v31, v13, 1, v15
	s_andn2_b64 s[64:65], s[40:41], s[30:31]
	v_cndmask_b32_e64 v23, v31, v23, s[30:31]
	v_addc_co_u32_e64 v7, s[30:31], 0, v7, s[30:31]
	v_addc_co_u32_e64 v13, s[64:65], 0, v13, s[64:65]
	s_mov_b64 exec, s[34:35]
	ds_write_b16 v14, v12
	s_mov_b64 exec, s[36:37]
	ds_write_b16 v16, v24
	s_mov_b64 exec, s[38:39]
	ds_write_b16 v22, v25
	s_mov_b64 exec, s[40:41]
	ds_write_b16 v23, v26
	s_mov_b64 exec, s[24:25]
	v_add_u32_e32 v12, 0x100, v12
	v_cmp_lt_u32_e64 s[0:1], v12, v5
	s_mov_b64 exec, s[0:1]
	s_cbranch_execnz .Lcp_loop
